# HGRN pass C: four row-per-lane dwordx2 output stores replaced by two dwordx4 via v_permlane32_swap pairs
# speedup vs baseline: 1.0080x; 1.0069x over previous
; __device__ __forceinline__ unsigned pk2(float lo, float hi) { f32x2 v = {lo, hi}; return __builtin_bit_cast(unsigned, __builtin_convertvector(v, bf16v2)); }
; template <bool OUT>
; __device__ void phase_hgrn(const Params& p, const bf16_t* Qh, const bf16_t* Vv, const _Float16* Lfb, bf16_t* Of, bf16_t* Ob, float* Sseg, float* Dlog, LAS unsigned char* lds) {
;     ...
;         if (c >= 4) {
;           const int row = rbase + sgn * (32 * tb + r);
;           bf16_t* op = (dir ? Ob + (size_t)(row - NCTX) * DM : Of + (size_t)row * DM) + h * 128 + 32 * dvb + 4 * hh;
; #pragma unroll
;           for (int g = 0; g < 4; ++g) {
;             u32x2 ov; ov.x = pk2(o[4 * g], o[4 * g + 1]); ov.y = pk2(o[4 * g + 2], o[4 * g + 3]);
;             *(u32x2*)(op + 8 * g) = ov;
;           }
.LBB0_2306:
	s_or_b64 exec, exec, s[0:1]
	ds_read_b128 v[140:143], v110
	ds_read_b128 v[144:147], v111
	ds_read_b128 v[148:151], v110 offset:32
	ds_read_b128 v[152:155], v111 offset:32
	v_mfma_f32_32x32x16_bf16 v[16:31], v[60:63], v[56:59], v[16:31]
	s_cmp_lt_u32 s34, 4
	s_waitcnt lgkmcnt(2)
	v_mfma_f32_32x32x16_bf16 v[32:47], v[140:143], v[144:147], v[32:47]
	s_waitcnt lgkmcnt(0)
	v_mfma_f32_32x32x16_bf16 v[32:47], v[148:151], v[152:155], v[32:47]
	ds_read_b128 v[140:143], v110 offset:64
	ds_read_b128 v[144:147], v111 offset:64
	ds_read_b128 v[148:151], v110 offset:96
	ds_read_b128 v[152:155], v111 offset:96
	s_waitcnt lgkmcnt(2)
	v_mfma_f32_32x32x16_bf16 v[32:47], v[140:143], v[144:147], v[32:47]
	s_waitcnt lgkmcnt(0)
	v_mfma_f32_32x32x16_bf16 v[32:47], v[148:151], v[152:155], v[32:47]
	ds_read_b128 v[140:143], v110 offset:128
	ds_read_b128 v[144:147], v111 offset:128
	ds_read_b128 v[148:151], v110 offset:160
	ds_read_b128 v[152:155], v111 offset:160
	s_waitcnt lgkmcnt(2)
	v_mfma_f32_32x32x16_bf16 v[32:47], v[140:143], v[144:147], v[32:47]
	s_waitcnt lgkmcnt(0)
	v_mfma_f32_32x32x16_bf16 v[32:47], v[148:151], v[152:155], v[32:47]
	ds_read_b128 v[140:143], v110 offset:192
	ds_read_b128 v[144:147], v111 offset:192
	ds_read_b128 v[148:151], v110 offset:224
	ds_read_b128 v[152:155], v111 offset:224
	s_waitcnt lgkmcnt(2)
	v_mfma_f32_32x32x16_bf16 v[32:47], v[140:143], v[144:147], v[32:47]
	s_waitcnt lgkmcnt(0)
	v_mfma_f32_32x32x16_bf16 v[32:47], v[148:151], v[152:155], v[32:47]
	s_waitcnt vmcnt(0)
	v_lshl_or_b32 v75, v197, 16, v196
	v_lshl_or_b32 v133, v199, 16, v198
	v_lshl_or_b32 v134, v201, 16, v200
	v_lshl_or_b32 v135, v203, 16, v202
	v_lshl_or_b32 v136, v205, 16, v204
	v_lshl_or_b32 v137, v207, 16, v206
	v_lshl_or_b32 v138, v209, 16, v208
	v_lshl_or_b32 v139, v211, 16, v210
	v_lshl_or_b32 v48, v213, 16, v212
	v_lshl_or_b32 v49, v215, 16, v214
	v_lshl_or_b32 v50, v217, 16, v216
	v_lshl_or_b32 v51, v219, 16, v218
	v_lshl_or_b32 v52, v221, 16, v220
	v_lshl_or_b32 v53, v223, 16, v222
	v_lshl_or_b32 v54, v225, 16, v224
	v_lshl_or_b32 v55, v227, 16, v226
	s_cbranch_scc1 .LBB0_2287
	v_add_u32_e32 v56, s3, v124
	v_add_u32_e32 v57, 0xfffffc00, v56
	v_cndmask_b32_e64 v56, v57, v56, s[50:51]
	v_ashrrev_i32_e32 v57, 31, v56
	v_lshlrev_b64 v[56:57], 11, v[56:57]
	v_lshl_add_u64 v[56:57], v[76:77], 0, v[56:57]
	s_nop 4
	v_mbcnt_lo_u32_b32 v58, -1, 0
	v_mbcnt_hi_u32_b32 v58, -1, v58
	v_and_b32_e32 v58, 32, v58
	v_lshrrev_b32_e32 v58, 2, v58
	v_mov_b32_e32 v59, 0
	v_lshl_add_u64 v[56:57], v[56:57], 0, v[58:59]
	v_cvt_pk_bf16_f32 v60, v32, v33
	v_cvt_pk_bf16_f32 v61, v34, v35
	v_cvt_pk_bf16_f32 v62, v36, v37
	v_cvt_pk_bf16_f32 v63, v38, v39
	s_nop 1
	v_permlane32_swap_b32 v60, v62
	v_permlane32_swap_b32 v61, v63
	global_store_dwordx4 v[56:57], v[60:63], off
	v_cvt_pk_bf16_f32 v32, v40, v41
	v_cvt_pk_bf16_f32 v33, v42, v43
	v_cvt_pk_bf16_f32 v34, v44, v45
	v_cvt_pk_bf16_f32 v35, v46, v47
	s_nop 1
	v_permlane32_swap_b32 v32, v34
	v_permlane32_swap_b32 v33, v35
	global_store_dwordx4 v[56:57], v[32:35], off offset:32
	s_branch .LBB0_2287
